# residual epilogues (kinds 12,14): accumulators lane-transposed first so residual loads AND stores are lane-contiguous; plus transposed slab stores (16,17-19); on top of v34
# speedup vs baseline: 1.0069x; 1.0069x over previous
; __device__ __forceinline__ void epilogue(const Params& p, const Unit& u, const f32x4 (&acc)[2][2][4][2], int wr, int wc, int fr, int fq) {
;     ...
;   } else {
;     const float* x1 = (const float*)(ws + WS_X1);
;     float* yo = (float*)(ws + WS_YPRE);
;     const int cb = u.pn * 256 + ct0;
; #pragma unroll
;     for (int ai = 0; ai < 2; ++ai)
; #pragma unroll
;       for (int mp = 0; mp < 2; ++mp) {
;         f32x4 xv[2][2][2];
; #pragma unroll
;         for (int mm = 0; mm < 2; ++mm) {
;           const size_t row = (size_t)(row0 + ai * 128 + (mp * 2 + mm) * 16);
; #pragma unroll
;           for (int bj = 0; bj < 2; ++bj)
; #pragma unroll
;             for (int n = 0; n < 2; ++n) xv[mm][bj][n] = *(const f32x4*)(x1 + row * 2048 + cb + bj * 128 + n * 16);
;         }
; #pragma unroll
;         for (int mm = 0; mm < 2; ++mm) {
;           const size_t row = (size_t)(row0 + ai * 128 + (mp * 2 + mm) * 16);
; #pragma unroll
;           for (int bj = 0; bj < 2; ++bj)
; #pragma unroll
;             for (int n = 0; n < 2; ++n) *(f32x4*)(yo + row * 2048 + cb + bj * 128 + n * 16) = xv[mm][bj][n] * ALPHA + acc[ai][bj][mp * 2 + mm][n];
;         }
;       }
.Le14_ep:
	v_lshrrev_b32_e32 v64, 2, v230
	v_and_b32_e32 v67, 3, v230
	v_lshlrev_b32_e32 v224, 6, v67
	v_lshl_add_u32 v224, v64, 2, v224
	v_and_b32_e32 v225, 64, v169
	v_add_u32_e32 v225, v225, v64
	v_lshl_add_u32 v225, s48, 8, v225
	v_lshlrev_b32_e32 v225, 13, v225
	v_and_b32_e32 v232, 0x60, v174
	v_lshl_add_u32 v232, v67, 2, v232
	v_lshl_or_b32 v232, s78, 8, v232
	v_lshl_add_u32 v225, v232, 2, v225
	s_add_u32 s34, s24, 0x109000
	s_addc_u32 s35, s25, 0
	s_add_u32 s36, s24, 0x13309000
	s_addc_u32 s37, s25, 0
	v_mov_b32_e32 v233, v225
	s_mov_b32 s30, 0x3f9837f0
	v_add_u32_e32 v235, 0x100000, v233
	global_load_dwordx4 v[132:135], v233, s[34:35] offset:0
	global_load_dwordx4 v[136:139], v233, s[34:35] offset:64
	global_load_dwordx4 v[140:143], v233, s[34:35] offset:512
	global_load_dwordx4 v[144:147], v233, s[34:35] offset:576
	v_add_u32_e32 v233, 0x20000, v233
	global_load_dwordx4 v[148:151], v233, s[34:35] offset:0
	global_load_dwordx4 v[152:155], v233, s[34:35] offset:64
	global_load_dwordx4 v[156:159], v233, s[34:35] offset:512
	global_load_dwordx4 v[160:163], v233, s[34:35] offset:576
	v_add_u32_e32 v233, 0x20000, v233
	global_load_dwordx4 v[164:167], v233, s[34:35] offset:0
	global_load_dwordx4 v[196:199], v233, s[34:35] offset:64
	global_load_dwordx4 v[200:203], v233, s[34:35] offset:512
	global_load_dwordx4 v[204:207], v233, s[34:35] offset:576
	v_add_u32_e32 v233, 0x20000, v233
	global_load_dwordx4 v[208:211], v233, s[34:35] offset:0
	global_load_dwordx4 v[212:215], v233, s[34:35] offset:64
	global_load_dwordx4 v[216:219], v233, s[34:35] offset:512
	global_load_dwordx4 v[220:223], v233, s[34:35] offset:576
	ds_bpermute_b32 v128, v224, v128
	ds_bpermute_b32 v129, v224, v129
	ds_bpermute_b32 v130, v224, v130
	ds_bpermute_b32 v131, v224, v131
	ds_bpermute_b32 v124, v224, v124
	ds_bpermute_b32 v125, v224, v125
	ds_bpermute_b32 v126, v224, v126
	ds_bpermute_b32 v127, v224, v127
	s_waitcnt vmcnt(15) lgkmcnt(4)
	v_fmac_f32_e32 v128, s30, v132
	v_fmac_f32_e32 v129, s30, v133
	v_fmac_f32_e32 v130, s30, v134
	v_fmac_f32_e32 v131, s30, v135
	global_store_dwordx4 v225, v[128:131], s[36:37] offset:0
	global_load_dwordx4 v[132:135], v235, s[34:35] offset:0
	ds_bpermute_b32 v96, v224, v96
	ds_bpermute_b32 v97, v224, v97
	ds_bpermute_b32 v98, v224, v98
	ds_bpermute_b32 v99, v224, v99
	s_waitcnt vmcnt(16) lgkmcnt(4)
	v_fmac_f32_e32 v124, s30, v136
	v_fmac_f32_e32 v125, s30, v137
	v_fmac_f32_e32 v126, s30, v138
	v_fmac_f32_e32 v127, s30, v139
	global_store_dwordx4 v225, v[124:127], s[36:37] offset:64
	global_load_dwordx4 v[136:139], v235, s[34:35] offset:64
	ds_bpermute_b32 v92, v224, v92
	ds_bpermute_b32 v93, v224, v93
	ds_bpermute_b32 v94, v224, v94
	ds_bpermute_b32 v95, v224, v95
	s_waitcnt vmcnt(17) lgkmcnt(4)
	v_fmac_f32_e32 v96, s30, v140
	v_fmac_f32_e32 v97, s30, v141
	v_fmac_f32_e32 v98, s30, v142
	v_fmac_f32_e32 v99, s30, v143
	global_store_dwordx4 v225, v[96:99], s[36:37] offset:512
	global_load_dwordx4 v[140:143], v235, s[34:35] offset:512
	ds_bpermute_b32 v120, v224, v120
	ds_bpermute_b32 v121, v224, v121
	ds_bpermute_b32 v122, v224, v122
	ds_bpermute_b32 v123, v224, v123
	s_waitcnt vmcnt(18) lgkmcnt(4)
	v_fmac_f32_e32 v92, s30, v144
	v_fmac_f32_e32 v93, s30, v145
	v_fmac_f32_e32 v94, s30, v146
	v_fmac_f32_e32 v95, s30, v147
	global_store_dwordx4 v225, v[92:95], s[36:37] offset:576
	v_add_u32_e32 v225, 0x20000, v225
	global_load_dwordx4 v[144:147], v235, s[34:35] offset:576
	v_add_u32_e32 v235, 0x20000, v235
	ds_bpermute_b32 v116, v224, v116
	ds_bpermute_b32 v117, v224, v117
	ds_bpermute_b32 v118, v224, v118
	ds_bpermute_b32 v119, v224, v119
	s_waitcnt vmcnt(19) lgkmcnt(4)
	v_fmac_f32_e32 v120, s30, v148
	v_fmac_f32_e32 v121, s30, v149
	v_fmac_f32_e32 v122, s30, v150
	v_fmac_f32_e32 v123, s30, v151
	global_store_dwordx4 v225, v[120:123], s[36:37] offset:0
	global_load_dwordx4 v[148:151], v235, s[34:35] offset:0
	ds_bpermute_b32 v88, v224, v88
	ds_bpermute_b32 v89, v224, v89
	ds_bpermute_b32 v90, v224, v90
	ds_bpermute_b32 v91, v224, v91
	s_waitcnt vmcnt(20) lgkmcnt(4)
	v_fmac_f32_e32 v116, s30, v152
	v_fmac_f32_e32 v117, s30, v153
	v_fmac_f32_e32 v118, s30, v154
	v_fmac_f32_e32 v119, s30, v155
	global_store_dwordx4 v225, v[116:119], s[36:37] offset:64
	global_load_dwordx4 v[152:155], v235, s[34:35] offset:64
	ds_bpermute_b32 v84, v224, v84
	ds_bpermute_b32 v85, v224, v85
	ds_bpermute_b32 v86, v224, v86
	ds_bpermute_b32 v87, v224, v87
	s_waitcnt vmcnt(21) lgkmcnt(4)
	v_fmac_f32_e32 v88, s30, v156
	v_fmac_f32_e32 v89, s30, v157
	v_fmac_f32_e32 v90, s30, v158
	v_fmac_f32_e32 v91, s30, v159
	global_store_dwordx4 v225, v[88:91], s[36:37] offset:512
	global_load_dwordx4 v[156:159], v235, s[34:35] offset:512
	ds_bpermute_b32 v112, v224, v112
	ds_bpermute_b32 v113, v224, v113
	ds_bpermute_b32 v114, v224, v114
	ds_bpermute_b32 v115, v224, v115
	s_waitcnt vmcnt(22) lgkmcnt(4)
	v_fmac_f32_e32 v84, s30, v160
	v_fmac_f32_e32 v85, s30, v161
	v_fmac_f32_e32 v86, s30, v162
	v_fmac_f32_e32 v87, s30, v163
	global_store_dwordx4 v225, v[84:87], s[36:37] offset:576
	v_add_u32_e32 v225, 0x20000, v225
	global_load_dwordx4 v[160:163], v235, s[34:35] offset:576
	v_add_u32_e32 v235, 0x20000, v235
	ds_bpermute_b32 v108, v224, v108
	ds_bpermute_b32 v109, v224, v109
	ds_bpermute_b32 v110, v224, v110
	ds_bpermute_b32 v111, v224, v111
	s_waitcnt vmcnt(23) lgkmcnt(4)
	v_fmac_f32_e32 v112, s30, v164
	v_fmac_f32_e32 v113, s30, v165
	v_fmac_f32_e32 v114, s30, v166
	v_fmac_f32_e32 v115, s30, v167
	global_store_dwordx4 v225, v[112:115], s[36:37] offset:0
	global_load_dwordx4 v[164:167], v235, s[34:35] offset:0
	ds_bpermute_b32 v80, v224, v80
	ds_bpermute_b32 v81, v224, v81
	ds_bpermute_b32 v82, v224, v82
	ds_bpermute_b32 v83, v224, v83
	s_waitcnt vmcnt(24) lgkmcnt(4)
; __device__ __forceinline__ void epilogue(const Params& p, const Unit& u, const f32x4 (&acc)[2][2][4][2], int wr, int wc, int fr, int fq) {
;     ...
;   } else {
;     const float* x1 = (const float*)(ws + WS_X1);
;     float* yo = (float*)(ws + WS_YPRE);
;     const int cb = u.pn * 256 + ct0;
; #pragma unroll
;     for (int ai = 0; ai < 2; ++ai)
; #pragma unroll
;       for (int mp = 0; mp < 2; ++mp) {
;         f32x4 xv[2][2][2];
; #pragma unroll
;         for (int mm = 0; mm < 2; ++mm) {
;           const size_t row = (size_t)(row0 + ai * 128 + (mp * 2 + mm) * 16);
; #pragma unroll
;           for (int bj = 0; bj < 2; ++bj)
; #pragma unroll
;             for (int n = 0; n < 2; ++n) xv[mm][bj][n] = *(const f32x4*)(x1 + row * 2048 + cb + bj * 128 + n * 16);
;         }
; #pragma unroll
;         for (int mm = 0; mm < 2; ++mm) {
;           const size_t row = (size_t)(row0 + ai * 128 + (mp * 2 + mm) * 16);
; #pragma unroll
;           for (int bj = 0; bj < 2; ++bj)
; #pragma unroll
;             for (int n = 0; n < 2; ++n) *(f32x4*)(yo + row * 2048 + cb + bj * 128 + n * 16) = xv[mm][bj][n] * ALPHA + acc[ai][bj][mp * 2 + mm][n];
;         }
;       }
	v_fmac_f32_e32 v108, s30, v196
	v_fmac_f32_e32 v109, s30, v197
	v_fmac_f32_e32 v110, s30, v198
	v_fmac_f32_e32 v111, s30, v199
	global_store_dwordx4 v225, v[108:111], s[36:37] offset:64
	global_load_dwordx4 v[196:199], v235, s[34:35] offset:64
	ds_bpermute_b32 v76, v224, v76
	ds_bpermute_b32 v77, v224, v77
	ds_bpermute_b32 v78, v224, v78
	ds_bpermute_b32 v79, v224, v79
	s_waitcnt vmcnt(25) lgkmcnt(4)
	v_fmac_f32_e32 v80, s30, v200
	v_fmac_f32_e32 v81, s30, v201
	v_fmac_f32_e32 v82, s30, v202
	v_fmac_f32_e32 v83, s30, v203
	global_store_dwordx4 v225, v[80:83], s[36:37] offset:512
	global_load_dwordx4 v[200:203], v235, s[34:35] offset:512
	ds_bpermute_b32 v104, v224, v104
	ds_bpermute_b32 v105, v224, v105
	ds_bpermute_b32 v106, v224, v106
	ds_bpermute_b32 v107, v224, v107
	s_waitcnt vmcnt(26) lgkmcnt(4)
	v_fmac_f32_e32 v76, s30, v204
	v_fmac_f32_e32 v77, s30, v205
	v_fmac_f32_e32 v78, s30, v206
	v_fmac_f32_e32 v79, s30, v207
	global_store_dwordx4 v225, v[76:79], s[36:37] offset:576
	v_add_u32_e32 v225, 0x20000, v225
	global_load_dwordx4 v[204:207], v235, s[34:35] offset:576
	v_add_u32_e32 v235, 0x20000, v235
	ds_bpermute_b32 v100, v224, v100
	ds_bpermute_b32 v101, v224, v101
	ds_bpermute_b32 v102, v224, v102
	ds_bpermute_b32 v103, v224, v103
	s_waitcnt vmcnt(27) lgkmcnt(4)
	v_fmac_f32_e32 v104, s30, v208
	v_fmac_f32_e32 v105, s30, v209
	v_fmac_f32_e32 v106, s30, v210
	v_fmac_f32_e32 v107, s30, v211
	global_store_dwordx4 v225, v[104:107], s[36:37] offset:0
	global_load_dwordx4 v[208:211], v235, s[34:35] offset:0
	ds_bpermute_b32 v72, v224, v72
	ds_bpermute_b32 v73, v224, v73
	ds_bpermute_b32 v74, v224, v74
	ds_bpermute_b32 v75, v224, v75
	s_waitcnt vmcnt(28) lgkmcnt(4)
	v_fmac_f32_e32 v100, s30, v212
	v_fmac_f32_e32 v101, s30, v213
	v_fmac_f32_e32 v102, s30, v214
	v_fmac_f32_e32 v103, s30, v215
	global_store_dwordx4 v225, v[100:103], s[36:37] offset:64
	global_load_dwordx4 v[212:215], v235, s[34:35] offset:64
	ds_bpermute_b32 v68, v224, v68
	ds_bpermute_b32 v69, v224, v69
	ds_bpermute_b32 v70, v224, v70
	ds_bpermute_b32 v71, v224, v71
	s_waitcnt vmcnt(29) lgkmcnt(4)
	v_fmac_f32_e32 v72, s30, v216
	v_fmac_f32_e32 v73, s30, v217
	v_fmac_f32_e32 v74, s30, v218
	v_fmac_f32_e32 v75, s30, v219
	global_store_dwordx4 v225, v[72:75], s[36:37] offset:512
	global_load_dwordx4 v[216:219], v235, s[34:35] offset:512
	ds_bpermute_b32 v60, v224, v60
	ds_bpermute_b32 v61, v224, v61
	ds_bpermute_b32 v62, v224, v62
	ds_bpermute_b32 v63, v224, v63
	s_waitcnt vmcnt(30) lgkmcnt(4)
	v_fmac_f32_e32 v68, s30, v220
	v_fmac_f32_e32 v69, s30, v221
	v_fmac_f32_e32 v70, s30, v222
	v_fmac_f32_e32 v71, s30, v223
	global_store_dwordx4 v225, v[68:71], s[36:37] offset:576
	v_add_u32_e32 v225, 0xa0000, v225
	global_load_dwordx4 v[220:223], v235, s[34:35] offset:576
	ds_bpermute_b32 v56, v224, v56
	ds_bpermute_b32 v57, v224, v57
	ds_bpermute_b32 v58, v224, v58
	ds_bpermute_b32 v59, v224, v59
	s_waitcnt vmcnt(30) lgkmcnt(4)
	v_fmac_f32_e32 v60, s30, v132
	v_fmac_f32_e32 v61, s30, v133
	v_fmac_f32_e32 v62, s30, v134
	v_fmac_f32_e32 v63, s30, v135
	global_store_dwordx4 v225, v[60:63], s[36:37] offset:0
	ds_bpermute_b32 v28, v224, v28
	ds_bpermute_b32 v29, v224, v29
	ds_bpermute_b32 v30, v224, v30
	ds_bpermute_b32 v31, v224, v31
	s_waitcnt vmcnt(29) lgkmcnt(4)
	v_fmac_f32_e32 v56, s30, v136
	v_fmac_f32_e32 v57, s30, v137
	v_fmac_f32_e32 v58, s30, v138
	v_fmac_f32_e32 v59, s30, v139
	global_store_dwordx4 v225, v[56:59], s[36:37] offset:64
	ds_bpermute_b32 v24, v224, v24
	ds_bpermute_b32 v25, v224, v25
	ds_bpermute_b32 v26, v224, v26
	ds_bpermute_b32 v27, v224, v27
	s_waitcnt vmcnt(28) lgkmcnt(4)
	v_fmac_f32_e32 v28, s30, v140
	v_fmac_f32_e32 v29, s30, v141
	v_fmac_f32_e32 v30, s30, v142
	v_fmac_f32_e32 v31, s30, v143
	global_store_dwordx4 v225, v[28:31], s[36:37] offset:512
	ds_bpermute_b32 v52, v224, v52
	ds_bpermute_b32 v53, v224, v53
	ds_bpermute_b32 v54, v224, v54
	ds_bpermute_b32 v55, v224, v55
	s_waitcnt vmcnt(27) lgkmcnt(4)
	v_fmac_f32_e32 v24, s30, v144
	v_fmac_f32_e32 v25, s30, v145
	v_fmac_f32_e32 v26, s30, v146
	v_fmac_f32_e32 v27, s30, v147
	global_store_dwordx4 v225, v[24:27], s[36:37] offset:576
	v_add_u32_e32 v225, 0x20000, v225
	ds_bpermute_b32 v48, v224, v48
	ds_bpermute_b32 v49, v224, v49
	ds_bpermute_b32 v50, v224, v50
	ds_bpermute_b32 v51, v224, v51
	s_waitcnt vmcnt(26) lgkmcnt(4)
	v_fmac_f32_e32 v52, s30, v148
	v_fmac_f32_e32 v53, s30, v149
	v_fmac_f32_e32 v54, s30, v150
	v_fmac_f32_e32 v55, s30, v151
	global_store_dwordx4 v225, v[52:55], s[36:37] offset:0
	ds_bpermute_b32 v20, v224, v20
	ds_bpermute_b32 v21, v224, v21
	ds_bpermute_b32 v22, v224, v22
	ds_bpermute_b32 v23, v224, v23
	s_waitcnt vmcnt(25) lgkmcnt(4)
	v_fmac_f32_e32 v48, s30, v152
	v_fmac_f32_e32 v49, s30, v153
	v_fmac_f32_e32 v50, s30, v154
	v_fmac_f32_e32 v51, s30, v155
	global_store_dwordx4 v225, v[48:51], s[36:37] offset:64
	ds_bpermute_b32 v16, v224, v16
	ds_bpermute_b32 v17, v224, v17
	ds_bpermute_b32 v18, v224, v18
	ds_bpermute_b32 v19, v224, v19
	s_waitcnt vmcnt(24) lgkmcnt(4)
	v_fmac_f32_e32 v20, s30, v156
	v_fmac_f32_e32 v21, s30, v157
	v_fmac_f32_e32 v22, s30, v158
	v_fmac_f32_e32 v23, s30, v159
	global_store_dwordx4 v225, v[20:23], s[36:37] offset:512
	ds_bpermute_b32 v44, v224, v44
	ds_bpermute_b32 v45, v224, v45
	ds_bpermute_b32 v46, v224, v46
	ds_bpermute_b32 v47, v224, v47
	s_waitcnt vmcnt(23) lgkmcnt(4)
	v_fmac_f32_e32 v16, s30, v160
	v_fmac_f32_e32 v17, s30, v161
	v_fmac_f32_e32 v18, s30, v162
	v_fmac_f32_e32 v19, s30, v163
	global_store_dwordx4 v225, v[16:19], s[36:37] offset:576
	v_add_u32_e32 v225, 0x20000, v225
	ds_bpermute_b32 v40, v224, v40
	ds_bpermute_b32 v41, v224, v41
	ds_bpermute_b32 v42, v224, v42
	ds_bpermute_b32 v43, v224, v43
	s_waitcnt vmcnt(22) lgkmcnt(4)
; __device__ __forceinline__ void epilogue(const Params& p, const Unit& u, const f32x4 (&acc)[2][2][4][2], int wr, int wc, int fr, int fq) {
;     ...
;   } else if (kind == 12) {
;     float* xo = (float*)(ws + WS_X1);
;     const int cb = u.pn * 256 + ct0;
; #pragma unroll
;     for (int ai = 0; ai < 2; ++ai)
; #pragma unroll
;       for (int mp = 0; mp < 2; ++mp) {
;         f32x4 xv[2][2][2];
; #pragma unroll
;         for (int mm = 0; mm < 2; ++mm) {
;           const int row = row0 + ai * 128 + (mp * 2 + mm) * 16;
;           const float* xr = row < TOKP ? p.in[0] + (size_t)row * 2048 : p.in[1] + (size_t)(row - TOKP) * 2048;
; #pragma unroll
;           for (int bj = 0; bj < 2; ++bj)
; #pragma unroll
;             for (int n = 0; n < 2; ++n) xv[mm][bj][n] = *(const f32x4*)(xr + cb + bj * 128 + n * 16);
;         }
; #pragma unroll
;         for (int mm = 0; mm < 2; ++mm) {
;           const int row = row0 + ai * 128 + (mp * 2 + mm) * 16;
; #pragma unroll
;           for (int bj = 0; bj < 2; ++bj)
; #pragma unroll
;             for (int n = 0; n < 2; ++n) *(f32x4*)(xo + (size_t)row * 2048 + cb + bj * 128 + n * 16) = xv[mm][bj][n] * ALPHA + acc[ai][bj][mp * 2 + mm][n];
;         }
;       }
;     ...
;   } else {
;     const float* x1 = (const float*)(ws + WS_X1);
;     float* yo = (float*)(ws + WS_YPRE);
;     const int cb = u.pn * 256 + ct0;
; #pragma unroll
;     for (int ai = 0; ai < 2; ++ai)
; #pragma unroll
;       for (int mp = 0; mp < 2; ++mp) {
;         f32x4 xv[2][2][2];
; #pragma unroll
;         for (int mm = 0; mm < 2; ++mm) {
;           const size_t row = (size_t)(row0 + ai * 128 + (mp * 2 + mm) * 16);
; #pragma unroll
;           for (int bj = 0; bj < 2; ++bj)
; #pragma unroll
;             for (int n = 0; n < 2; ++n) xv[mm][bj][n] = *(const f32x4*)(x1 + row * 2048 + cb + bj * 128 + n * 16);
;         }
; #pragma unroll
;         for (int mm = 0; mm < 2; ++mm) {
;           const size_t row = (size_t)(row0 + ai * 128 + (mp * 2 + mm) * 16);
; #pragma unroll
;           for (int bj = 0; bj < 2; ++bj)
; #pragma unroll
;             for (int n = 0; n < 2; ++n) *(f32x4*)(yo + row * 2048 + cb + bj * 128 + n * 16) = xv[mm][bj][n] * ALPHA + acc[ai][bj][mp * 2 + mm][n];
;         }
;       }
	v_fmac_f32_e32 v44, s30, v164
	v_fmac_f32_e32 v45, s30, v165
	v_fmac_f32_e32 v46, s30, v166
	v_fmac_f32_e32 v47, s30, v167
	global_store_dwordx4 v225, v[44:47], s[36:37] offset:0
	ds_bpermute_b32 v12, v224, v12
	ds_bpermute_b32 v13, v224, v13
	ds_bpermute_b32 v14, v224, v14
	ds_bpermute_b32 v15, v224, v15
	s_waitcnt vmcnt(21) lgkmcnt(4)
	v_fmac_f32_e32 v40, s30, v196
	v_fmac_f32_e32 v41, s30, v197
	v_fmac_f32_e32 v42, s30, v198
	v_fmac_f32_e32 v43, s30, v199
	global_store_dwordx4 v225, v[40:43], s[36:37] offset:64
	ds_bpermute_b32 v8, v224, v8
	ds_bpermute_b32 v9, v224, v9
	ds_bpermute_b32 v10, v224, v10
	ds_bpermute_b32 v11, v224, v11
	s_waitcnt vmcnt(20) lgkmcnt(4)
	v_fmac_f32_e32 v12, s30, v200
	v_fmac_f32_e32 v13, s30, v201
	v_fmac_f32_e32 v14, s30, v202
	v_fmac_f32_e32 v15, s30, v203
	global_store_dwordx4 v225, v[12:15], s[36:37] offset:512
	ds_bpermute_b32 v36, v224, v36
	ds_bpermute_b32 v37, v224, v37
	ds_bpermute_b32 v38, v224, v38
	ds_bpermute_b32 v39, v224, v39
	s_waitcnt vmcnt(19) lgkmcnt(4)
	v_fmac_f32_e32 v8, s30, v204
	v_fmac_f32_e32 v9, s30, v205
	v_fmac_f32_e32 v10, s30, v206
	v_fmac_f32_e32 v11, s30, v207
	global_store_dwordx4 v225, v[8:11], s[36:37] offset:576
	v_add_u32_e32 v225, 0x20000, v225
	ds_bpermute_b32 v32, v224, v32
	ds_bpermute_b32 v33, v224, v33
	ds_bpermute_b32 v34, v224, v34
	ds_bpermute_b32 v35, v224, v35
	s_waitcnt vmcnt(18) lgkmcnt(4)
	v_fmac_f32_e32 v36, s30, v208
	v_fmac_f32_e32 v37, s30, v209
	v_fmac_f32_e32 v38, s30, v210
	v_fmac_f32_e32 v39, s30, v211
	global_store_dwordx4 v225, v[36:39], s[36:37] offset:0
	ds_bpermute_b32 v4, v224, v4
	ds_bpermute_b32 v5, v224, v5
	ds_bpermute_b32 v6, v224, v6
	ds_bpermute_b32 v7, v224, v7
	s_waitcnt vmcnt(17) lgkmcnt(4)
	v_fmac_f32_e32 v32, s30, v212
	v_fmac_f32_e32 v33, s30, v213
	v_fmac_f32_e32 v34, s30, v214
	v_fmac_f32_e32 v35, s30, v215
	global_store_dwordx4 v225, v[32:35], s[36:37] offset:64
	ds_bpermute_b32 v0, v224, v0
	ds_bpermute_b32 v1, v224, v1
	ds_bpermute_b32 v2, v224, v2
	ds_bpermute_b32 v3, v224, v3
	s_waitcnt vmcnt(16) lgkmcnt(4)
	v_fmac_f32_e32 v4, s30, v216
	v_fmac_f32_e32 v5, s30, v217
	v_fmac_f32_e32 v6, s30, v218
	v_fmac_f32_e32 v7, s30, v219
	global_store_dwordx4 v225, v[4:7], s[36:37] offset:512
	s_waitcnt vmcnt(15) lgkmcnt(0)
	v_fmac_f32_e32 v0, s30, v220
	v_fmac_f32_e32 v1, s30, v221
	v_fmac_f32_e32 v2, s30, v222
	v_fmac_f32_e32 v3, s30, v223
	global_store_dwordx4 v225, v[0:3], s[36:37] offset:576
	s_branch .LBB0_987
.Le12_ep:
	v_lshrrev_b32_e32 v64, 2, v230
	v_and_b32_e32 v67, 3, v230
	v_lshlrev_b32_e32 v224, 6, v67
	v_lshl_add_u32 v224, v64, 2, v224
	v_and_b32_e32 v225, 64, v169
	v_add_u32_e32 v225, v225, v64
	v_lshl_add_u32 v225, s48, 8, v225
	v_lshlrev_b32_e32 v225, 13, v225
	v_and_b32_e32 v232, 0x60, v174
	v_lshl_add_u32 v232, v67, 2, v232
	v_lshl_or_b32 v232, s78, 8, v232
	v_lshl_add_u32 v225, v232, 2, v225
	s_add_u32 s36, s24, 0x109000
	s_addc_u32 s37, s25, 0
	s_mov_b64 s[34:35], s[4:5]
	v_mov_b32_e32 v233, v225
	s_cmp_lt_u32 s48, 32
	s_cbranch_scc1 .Le12_ep_p
	s_mov_b64 s[34:35], s[6:7]
	v_add_u32_e32 v233, 0xfc000000, v225
.Le12_ep_p:
	s_mov_b32 s30, 0x3f9837f0
	v_add_u32_e32 v235, 0x100000, v233
	global_load_dwordx4 v[132:135], v233, s[34:35] offset:0
	global_load_dwordx4 v[136:139], v233, s[34:35] offset:64
	global_load_dwordx4 v[140:143], v233, s[34:35] offset:512
	global_load_dwordx4 v[144:147], v233, s[34:35] offset:576
	v_add_u32_e32 v233, 0x20000, v233
	global_load_dwordx4 v[148:151], v233, s[34:35] offset:0
	global_load_dwordx4 v[152:155], v233, s[34:35] offset:64
	global_load_dwordx4 v[156:159], v233, s[34:35] offset:512
	global_load_dwordx4 v[160:163], v233, s[34:35] offset:576
	v_add_u32_e32 v233, 0x20000, v233
	global_load_dwordx4 v[164:167], v233, s[34:35] offset:0
	global_load_dwordx4 v[196:199], v233, s[34:35] offset:64
	global_load_dwordx4 v[200:203], v233, s[34:35] offset:512
	global_load_dwordx4 v[204:207], v233, s[34:35] offset:576
	v_add_u32_e32 v233, 0x20000, v233
	global_load_dwordx4 v[208:211], v233, s[34:35] offset:0
	global_load_dwordx4 v[212:215], v233, s[34:35] offset:64
	global_load_dwordx4 v[216:219], v233, s[34:35] offset:512
	global_load_dwordx4 v[220:223], v233, s[34:35] offset:576
	ds_bpermute_b32 v128, v224, v128
	ds_bpermute_b32 v129, v224, v129
	ds_bpermute_b32 v130, v224, v130
	ds_bpermute_b32 v131, v224, v131
	ds_bpermute_b32 v124, v224, v124
	ds_bpermute_b32 v125, v224, v125
	ds_bpermute_b32 v126, v224, v126
	ds_bpermute_b32 v127, v224, v127
	s_waitcnt vmcnt(15) lgkmcnt(4)
	v_fmac_f32_e32 v128, s30, v132
	v_fmac_f32_e32 v129, s30, v133
	v_fmac_f32_e32 v130, s30, v134
	v_fmac_f32_e32 v131, s30, v135
	global_store_dwordx4 v225, v[128:131], s[36:37] offset:0
	global_load_dwordx4 v[132:135], v235, s[34:35] offset:0
	ds_bpermute_b32 v96, v224, v96
	ds_bpermute_b32 v97, v224, v97
	ds_bpermute_b32 v98, v224, v98
	ds_bpermute_b32 v99, v224, v99
	s_waitcnt vmcnt(16) lgkmcnt(4)
	v_fmac_f32_e32 v124, s30, v136
	v_fmac_f32_e32 v125, s30, v137
	v_fmac_f32_e32 v126, s30, v138
	v_fmac_f32_e32 v127, s30, v139
	global_store_dwordx4 v225, v[124:127], s[36:37] offset:64
	global_load_dwordx4 v[136:139], v235, s[34:35] offset:64
	ds_bpermute_b32 v92, v224, v92
	ds_bpermute_b32 v93, v224, v93
	ds_bpermute_b32 v94, v224, v94
	ds_bpermute_b32 v95, v224, v95
	s_waitcnt vmcnt(17) lgkmcnt(4)
	v_fmac_f32_e32 v96, s30, v140
	v_fmac_f32_e32 v97, s30, v141
	v_fmac_f32_e32 v98, s30, v142
	v_fmac_f32_e32 v99, s30, v143
	global_store_dwordx4 v225, v[96:99], s[36:37] offset:512
	global_load_dwordx4 v[140:143], v235, s[34:35] offset:512
	ds_bpermute_b32 v120, v224, v120
	ds_bpermute_b32 v121, v224, v121
	ds_bpermute_b32 v122, v224, v122
	ds_bpermute_b32 v123, v224, v123
	s_waitcnt vmcnt(18) lgkmcnt(4)
; __device__ __forceinline__ void epilogue(const Params& p, const Unit& u, const f32x4 (&acc)[2][2][4][2], int wr, int wc, int fr, int fq) {
;     ...
;   } else if (kind == 12) {
;     float* xo = (float*)(ws + WS_X1);
;     const int cb = u.pn * 256 + ct0;
; #pragma unroll
;     for (int ai = 0; ai < 2; ++ai)
; #pragma unroll
;       for (int mp = 0; mp < 2; ++mp) {
;         f32x4 xv[2][2][2];
; #pragma unroll
;         for (int mm = 0; mm < 2; ++mm) {
;           const int row = row0 + ai * 128 + (mp * 2 + mm) * 16;
;           const float* xr = row < TOKP ? p.in[0] + (size_t)row * 2048 : p.in[1] + (size_t)(row - TOKP) * 2048;
; #pragma unroll
;           for (int bj = 0; bj < 2; ++bj)
; #pragma unroll
;             for (int n = 0; n < 2; ++n) xv[mm][bj][n] = *(const f32x4*)(xr + cb + bj * 128 + n * 16);
;         }
; #pragma unroll
;         for (int mm = 0; mm < 2; ++mm) {
;           const int row = row0 + ai * 128 + (mp * 2 + mm) * 16;
; #pragma unroll
;           for (int bj = 0; bj < 2; ++bj)
; #pragma unroll
;             for (int n = 0; n < 2; ++n) *(f32x4*)(xo + (size_t)row * 2048 + cb + bj * 128 + n * 16) = xv[mm][bj][n] * ALPHA + acc[ai][bj][mp * 2 + mm][n];
;         }
;       }
	v_fmac_f32_e32 v92, s30, v144
	v_fmac_f32_e32 v93, s30, v145
	v_fmac_f32_e32 v94, s30, v146
	v_fmac_f32_e32 v95, s30, v147
	global_store_dwordx4 v225, v[92:95], s[36:37] offset:576
	v_add_u32_e32 v225, 0x20000, v225
	global_load_dwordx4 v[144:147], v235, s[34:35] offset:576
	v_add_u32_e32 v235, 0x20000, v235
	ds_bpermute_b32 v116, v224, v116
	ds_bpermute_b32 v117, v224, v117
	ds_bpermute_b32 v118, v224, v118
	ds_bpermute_b32 v119, v224, v119
	s_waitcnt vmcnt(19) lgkmcnt(4)
	v_fmac_f32_e32 v120, s30, v148
	v_fmac_f32_e32 v121, s30, v149
	v_fmac_f32_e32 v122, s30, v150
	v_fmac_f32_e32 v123, s30, v151
	global_store_dwordx4 v225, v[120:123], s[36:37] offset:0
	global_load_dwordx4 v[148:151], v235, s[34:35] offset:0
	ds_bpermute_b32 v88, v224, v88
	ds_bpermute_b32 v89, v224, v89
	ds_bpermute_b32 v90, v224, v90
	ds_bpermute_b32 v91, v224, v91
	s_waitcnt vmcnt(20) lgkmcnt(4)
	v_fmac_f32_e32 v116, s30, v152
	v_fmac_f32_e32 v117, s30, v153
	v_fmac_f32_e32 v118, s30, v154
	v_fmac_f32_e32 v119, s30, v155
	global_store_dwordx4 v225, v[116:119], s[36:37] offset:64
	global_load_dwordx4 v[152:155], v235, s[34:35] offset:64
	ds_bpermute_b32 v84, v224, v84
	ds_bpermute_b32 v85, v224, v85
	ds_bpermute_b32 v86, v224, v86
	ds_bpermute_b32 v87, v224, v87
	s_waitcnt vmcnt(21) lgkmcnt(4)
	v_fmac_f32_e32 v88, s30, v156
	v_fmac_f32_e32 v89, s30, v157
	v_fmac_f32_e32 v90, s30, v158
	v_fmac_f32_e32 v91, s30, v159
	global_store_dwordx4 v225, v[88:91], s[36:37] offset:512
	global_load_dwordx4 v[156:159], v235, s[34:35] offset:512
	ds_bpermute_b32 v112, v224, v112
	ds_bpermute_b32 v113, v224, v113
	ds_bpermute_b32 v114, v224, v114
	ds_bpermute_b32 v115, v224, v115
	s_waitcnt vmcnt(22) lgkmcnt(4)
	v_fmac_f32_e32 v84, s30, v160
	v_fmac_f32_e32 v85, s30, v161
	v_fmac_f32_e32 v86, s30, v162
	v_fmac_f32_e32 v87, s30, v163
	global_store_dwordx4 v225, v[84:87], s[36:37] offset:576
	v_add_u32_e32 v225, 0x20000, v225
	global_load_dwordx4 v[160:163], v235, s[34:35] offset:576
	v_add_u32_e32 v235, 0x20000, v235
	ds_bpermute_b32 v108, v224, v108
	ds_bpermute_b32 v109, v224, v109
	ds_bpermute_b32 v110, v224, v110
	ds_bpermute_b32 v111, v224, v111
	s_waitcnt vmcnt(23) lgkmcnt(4)
	v_fmac_f32_e32 v112, s30, v164
	v_fmac_f32_e32 v113, s30, v165
	v_fmac_f32_e32 v114, s30, v166
	v_fmac_f32_e32 v115, s30, v167
	global_store_dwordx4 v225, v[112:115], s[36:37] offset:0
	global_load_dwordx4 v[164:167], v235, s[34:35] offset:0
	ds_bpermute_b32 v80, v224, v80
	ds_bpermute_b32 v81, v224, v81
	ds_bpermute_b32 v82, v224, v82
	ds_bpermute_b32 v83, v224, v83
	s_waitcnt vmcnt(24) lgkmcnt(4)
	v_fmac_f32_e32 v108, s30, v196
	v_fmac_f32_e32 v109, s30, v197
	v_fmac_f32_e32 v110, s30, v198
	v_fmac_f32_e32 v111, s30, v199
	global_store_dwordx4 v225, v[108:111], s[36:37] offset:64
	global_load_dwordx4 v[196:199], v235, s[34:35] offset:64
	ds_bpermute_b32 v76, v224, v76
	ds_bpermute_b32 v77, v224, v77
	ds_bpermute_b32 v78, v224, v78
	ds_bpermute_b32 v79, v224, v79
	s_waitcnt vmcnt(25) lgkmcnt(4)
	v_fmac_f32_e32 v80, s30, v200
	v_fmac_f32_e32 v81, s30, v201
	v_fmac_f32_e32 v82, s30, v202
	v_fmac_f32_e32 v83, s30, v203
	global_store_dwordx4 v225, v[80:83], s[36:37] offset:512
	global_load_dwordx4 v[200:203], v235, s[34:35] offset:512
	ds_bpermute_b32 v104, v224, v104
	ds_bpermute_b32 v105, v224, v105
	ds_bpermute_b32 v106, v224, v106
	ds_bpermute_b32 v107, v224, v107
	s_waitcnt vmcnt(26) lgkmcnt(4)
	v_fmac_f32_e32 v76, s30, v204
	v_fmac_f32_e32 v77, s30, v205
	v_fmac_f32_e32 v78, s30, v206
	v_fmac_f32_e32 v79, s30, v207
	global_store_dwordx4 v225, v[76:79], s[36:37] offset:576
	v_add_u32_e32 v225, 0x20000, v225
	global_load_dwordx4 v[204:207], v235, s[34:35] offset:576
	v_add_u32_e32 v235, 0x20000, v235
	ds_bpermute_b32 v100, v224, v100
	ds_bpermute_b32 v101, v224, v101
	ds_bpermute_b32 v102, v224, v102
	ds_bpermute_b32 v103, v224, v103
	s_waitcnt vmcnt(27) lgkmcnt(4)
	v_fmac_f32_e32 v104, s30, v208
	v_fmac_f32_e32 v105, s30, v209
	v_fmac_f32_e32 v106, s30, v210
	v_fmac_f32_e32 v107, s30, v211
	global_store_dwordx4 v225, v[104:107], s[36:37] offset:0
	global_load_dwordx4 v[208:211], v235, s[34:35] offset:0
	ds_bpermute_b32 v72, v224, v72
	ds_bpermute_b32 v73, v224, v73
	ds_bpermute_b32 v74, v224, v74
	ds_bpermute_b32 v75, v224, v75
	s_waitcnt vmcnt(28) lgkmcnt(4)
	v_fmac_f32_e32 v100, s30, v212
	v_fmac_f32_e32 v101, s30, v213
	v_fmac_f32_e32 v102, s30, v214
	v_fmac_f32_e32 v103, s30, v215
	global_store_dwordx4 v225, v[100:103], s[36:37] offset:64
	global_load_dwordx4 v[212:215], v235, s[34:35] offset:64
	ds_bpermute_b32 v68, v224, v68
	ds_bpermute_b32 v69, v224, v69
	ds_bpermute_b32 v70, v224, v70
	ds_bpermute_b32 v71, v224, v71
	s_waitcnt vmcnt(29) lgkmcnt(4)
	v_fmac_f32_e32 v72, s30, v216
	v_fmac_f32_e32 v73, s30, v217
	v_fmac_f32_e32 v74, s30, v218
	v_fmac_f32_e32 v75, s30, v219
	global_store_dwordx4 v225, v[72:75], s[36:37] offset:512
	global_load_dwordx4 v[216:219], v235, s[34:35] offset:512
	ds_bpermute_b32 v60, v224, v60
	ds_bpermute_b32 v61, v224, v61
	ds_bpermute_b32 v62, v224, v62
	ds_bpermute_b32 v63, v224, v63
	s_waitcnt vmcnt(30) lgkmcnt(4)
	v_fmac_f32_e32 v68, s30, v220
	v_fmac_f32_e32 v69, s30, v221
	v_fmac_f32_e32 v70, s30, v222
	v_fmac_f32_e32 v71, s30, v223
	global_store_dwordx4 v225, v[68:71], s[36:37] offset:576
	v_add_u32_e32 v225, 0xa0000, v225
	global_load_dwordx4 v[220:223], v235, s[34:35] offset:576
	ds_bpermute_b32 v56, v224, v56
	ds_bpermute_b32 v57, v224, v57
	ds_bpermute_b32 v58, v224, v58
	ds_bpermute_b32 v59, v224, v59
	s_waitcnt vmcnt(30) lgkmcnt(4)
; __device__ __forceinline__ void epilogue(const Params& p, const Unit& u, const f32x4 (&acc)[2][2][4][2], int wr, int wc, int fr, int fq) {
;     ...
;   } else if (kind == 12) {
;     float* xo = (float*)(ws + WS_X1);
;     const int cb = u.pn * 256 + ct0;
; #pragma unroll
;     for (int ai = 0; ai < 2; ++ai)
; #pragma unroll
;       for (int mp = 0; mp < 2; ++mp) {
;         f32x4 xv[2][2][2];
; #pragma unroll
;         for (int mm = 0; mm < 2; ++mm) {
;           const int row = row0 + ai * 128 + (mp * 2 + mm) * 16;
;           const float* xr = row < TOKP ? p.in[0] + (size_t)row * 2048 : p.in[1] + (size_t)(row - TOKP) * 2048;
; #pragma unroll
;           for (int bj = 0; bj < 2; ++bj)
; #pragma unroll
;             for (int n = 0; n < 2; ++n) xv[mm][bj][n] = *(const f32x4*)(xr + cb + bj * 128 + n * 16);
;         }
; #pragma unroll
;         for (int mm = 0; mm < 2; ++mm) {
;           const int row = row0 + ai * 128 + (mp * 2 + mm) * 16;
; #pragma unroll
;           for (int bj = 0; bj < 2; ++bj)
; #pragma unroll
;             for (int n = 0; n < 2; ++n) *(f32x4*)(xo + (size_t)row * 2048 + cb + bj * 128 + n * 16) = xv[mm][bj][n] * ALPHA + acc[ai][bj][mp * 2 + mm][n];
;         }
;       }
	v_fmac_f32_e32 v60, s30, v132
	v_fmac_f32_e32 v61, s30, v133
	v_fmac_f32_e32 v62, s30, v134
	v_fmac_f32_e32 v63, s30, v135
	global_store_dwordx4 v225, v[60:63], s[36:37] offset:0
	ds_bpermute_b32 v28, v224, v28
	ds_bpermute_b32 v29, v224, v29
	ds_bpermute_b32 v30, v224, v30
	ds_bpermute_b32 v31, v224, v31
	s_waitcnt vmcnt(29) lgkmcnt(4)
	v_fmac_f32_e32 v56, s30, v136
	v_fmac_f32_e32 v57, s30, v137
	v_fmac_f32_e32 v58, s30, v138
	v_fmac_f32_e32 v59, s30, v139
	global_store_dwordx4 v225, v[56:59], s[36:37] offset:64
	ds_bpermute_b32 v24, v224, v24
	ds_bpermute_b32 v25, v224, v25
	ds_bpermute_b32 v26, v224, v26
	ds_bpermute_b32 v27, v224, v27
	s_waitcnt vmcnt(28) lgkmcnt(4)
	v_fmac_f32_e32 v28, s30, v140
	v_fmac_f32_e32 v29, s30, v141
	v_fmac_f32_e32 v30, s30, v142
	v_fmac_f32_e32 v31, s30, v143
	global_store_dwordx4 v225, v[28:31], s[36:37] offset:512
	ds_bpermute_b32 v52, v224, v52
	ds_bpermute_b32 v53, v224, v53
	ds_bpermute_b32 v54, v224, v54
	ds_bpermute_b32 v55, v224, v55
	s_waitcnt vmcnt(27) lgkmcnt(4)
	v_fmac_f32_e32 v24, s30, v144
	v_fmac_f32_e32 v25, s30, v145
	v_fmac_f32_e32 v26, s30, v146
	v_fmac_f32_e32 v27, s30, v147
	global_store_dwordx4 v225, v[24:27], s[36:37] offset:576
	v_add_u32_e32 v225, 0x20000, v225
	ds_bpermute_b32 v48, v224, v48
	ds_bpermute_b32 v49, v224, v49
	ds_bpermute_b32 v50, v224, v50
	ds_bpermute_b32 v51, v224, v51
	s_waitcnt vmcnt(26) lgkmcnt(4)
	v_fmac_f32_e32 v52, s30, v148
	v_fmac_f32_e32 v53, s30, v149
	v_fmac_f32_e32 v54, s30, v150
	v_fmac_f32_e32 v55, s30, v151
	global_store_dwordx4 v225, v[52:55], s[36:37] offset:0
	ds_bpermute_b32 v20, v224, v20
	ds_bpermute_b32 v21, v224, v21
	ds_bpermute_b32 v22, v224, v22
	ds_bpermute_b32 v23, v224, v23
	s_waitcnt vmcnt(25) lgkmcnt(4)
	v_fmac_f32_e32 v48, s30, v152
	v_fmac_f32_e32 v49, s30, v153
	v_fmac_f32_e32 v50, s30, v154
	v_fmac_f32_e32 v51, s30, v155
	global_store_dwordx4 v225, v[48:51], s[36:37] offset:64
	ds_bpermute_b32 v16, v224, v16
	ds_bpermute_b32 v17, v224, v17
	ds_bpermute_b32 v18, v224, v18
	ds_bpermute_b32 v19, v224, v19
	s_waitcnt vmcnt(24) lgkmcnt(4)
	v_fmac_f32_e32 v20, s30, v156
	v_fmac_f32_e32 v21, s30, v157
	v_fmac_f32_e32 v22, s30, v158
	v_fmac_f32_e32 v23, s30, v159
	global_store_dwordx4 v225, v[20:23], s[36:37] offset:512
	ds_bpermute_b32 v44, v224, v44
	ds_bpermute_b32 v45, v224, v45
	ds_bpermute_b32 v46, v224, v46
	ds_bpermute_b32 v47, v224, v47
	s_waitcnt vmcnt(23) lgkmcnt(4)
	v_fmac_f32_e32 v16, s30, v160
	v_fmac_f32_e32 v17, s30, v161
	v_fmac_f32_e32 v18, s30, v162
	v_fmac_f32_e32 v19, s30, v163
	global_store_dwordx4 v225, v[16:19], s[36:37] offset:576
	v_add_u32_e32 v225, 0x20000, v225
	ds_bpermute_b32 v40, v224, v40
	ds_bpermute_b32 v41, v224, v41
	ds_bpermute_b32 v42, v224, v42
	ds_bpermute_b32 v43, v224, v43
	s_waitcnt vmcnt(22) lgkmcnt(4)
	v_fmac_f32_e32 v44, s30, v164
	v_fmac_f32_e32 v45, s30, v165
	v_fmac_f32_e32 v46, s30, v166
	v_fmac_f32_e32 v47, s30, v167
	global_store_dwordx4 v225, v[44:47], s[36:37] offset:0
	ds_bpermute_b32 v12, v224, v12
	ds_bpermute_b32 v13, v224, v13
	ds_bpermute_b32 v14, v224, v14
	ds_bpermute_b32 v15, v224, v15
	s_waitcnt vmcnt(21) lgkmcnt(4)
	v_fmac_f32_e32 v40, s30, v196
	v_fmac_f32_e32 v41, s30, v197
	v_fmac_f32_e32 v42, s30, v198
	v_fmac_f32_e32 v43, s30, v199
	global_store_dwordx4 v225, v[40:43], s[36:37] offset:64
	ds_bpermute_b32 v8, v224, v8
	ds_bpermute_b32 v9, v224, v9
	ds_bpermute_b32 v10, v224, v10
	ds_bpermute_b32 v11, v224, v11
	s_waitcnt vmcnt(20) lgkmcnt(4)
	v_fmac_f32_e32 v12, s30, v200
	v_fmac_f32_e32 v13, s30, v201
	v_fmac_f32_e32 v14, s30, v202
	v_fmac_f32_e32 v15, s30, v203
	global_store_dwordx4 v225, v[12:15], s[36:37] offset:512
	ds_bpermute_b32 v36, v224, v36
	ds_bpermute_b32 v37, v224, v37
	ds_bpermute_b32 v38, v224, v38
	ds_bpermute_b32 v39, v224, v39
	s_waitcnt vmcnt(19) lgkmcnt(4)
	v_fmac_f32_e32 v8, s30, v204
	v_fmac_f32_e32 v9, s30, v205
	v_fmac_f32_e32 v10, s30, v206
	v_fmac_f32_e32 v11, s30, v207
	global_store_dwordx4 v225, v[8:11], s[36:37] offset:576
	v_add_u32_e32 v225, 0x20000, v225
	ds_bpermute_b32 v32, v224, v32
	ds_bpermute_b32 v33, v224, v33
	ds_bpermute_b32 v34, v224, v34
	ds_bpermute_b32 v35, v224, v35
	s_waitcnt vmcnt(18) lgkmcnt(4)
	v_fmac_f32_e32 v36, s30, v208
	v_fmac_f32_e32 v37, s30, v209
	v_fmac_f32_e32 v38, s30, v210
	v_fmac_f32_e32 v39, s30, v211
	global_store_dwordx4 v225, v[36:39], s[36:37] offset:0
	ds_bpermute_b32 v4, v224, v4
	ds_bpermute_b32 v5, v224, v5
	ds_bpermute_b32 v6, v224, v6
	ds_bpermute_b32 v7, v224, v7
	s_waitcnt vmcnt(17) lgkmcnt(4)
	v_fmac_f32_e32 v32, s30, v212
	v_fmac_f32_e32 v33, s30, v213
	v_fmac_f32_e32 v34, s30, v214
	v_fmac_f32_e32 v35, s30, v215
	global_store_dwordx4 v225, v[32:35], s[36:37] offset:64
	ds_bpermute_b32 v0, v224, v0
	ds_bpermute_b32 v1, v224, v1
	ds_bpermute_b32 v2, v224, v2
	ds_bpermute_b32 v3, v224, v3
	s_waitcnt vmcnt(16) lgkmcnt(4)
	v_fmac_f32_e32 v4, s30, v216
	v_fmac_f32_e32 v5, s30, v217
	v_fmac_f32_e32 v6, s30, v218
	v_fmac_f32_e32 v7, s30, v219
	global_store_dwordx4 v225, v[4:7], s[36:37] offset:512
	s_waitcnt vmcnt(15) lgkmcnt(0)
	v_fmac_f32_e32 v0, s30, v220
	v_fmac_f32_e32 v1, s30, v221
	v_fmac_f32_e32 v2, s30, v222
	v_fmac_f32_e32 v3, s30, v223
	global_store_dwordx4 v225, v[0:3], s[36:37] offset:576
	s_branch .LBB0_987
